# ret-in epilogue rope path: all cos/sin loads issued ahead (4 groups in flight), all stores after the last load wait; plus early low-prio MFMAs and deferred retention epilogue
# baseline (speedup 1.0000x reference)
.LBB0_503:
	s_and_b64 vcc, exec, s[6:7]
	s_cbranch_vccz .LBB0_505
	s_cmp_lt_i32 s40, 8
	s_cselect_b64 vcc, -1, 0
	s_and_b64 s[6:7], vcc, exec
	s_cselect_b32 s3, s60, s62
	s_cselect_b32 s6, s57, s61
	s_and_b32 s7, s14, 0x700
	s_lshl_b32 s7, s7, 1
	s_add_u32 s6, s6, s7
	v_lshlrev_b32_e32 v146, 1, v148
	s_addc_u32 s7, s3, 0
	v_cndmask_b32_e32 v134, 1.0, v173, vcc
	v_lshl_add_u64 v[166:167], s[6:7], 0, v[146:147]
	v_mov_b32_e32 v246, v164
	v_ashrrev_i32_e32 v247, 31, v246
	v_lshlrev_b64 v[248:249], 9, v[246:247]
	v_lshl_add_u64 v[250:251], v[152:153], 0, v[248:249]
	v_lshl_add_u64 v[252:253], v[150:151], 0, v[248:249]
	global_load_dwordx4 v[174:177], v[250:251], off
	global_load_dwordx4 v[178:181], v[250:251], off offset:16
	global_load_dwordx4 v[182:185], v[252:253], off
	global_load_dwordx4 v[186:189], v[252:253], off offset:16
	v_add_u32_e32 v246, 16, v164
	v_ashrrev_i32_e32 v247, 31, v246
	v_lshlrev_b64 v[248:249], 9, v[246:247]
	v_lshl_add_u64 v[250:251], v[152:153], 0, v[248:249]
	v_lshl_add_u64 v[252:253], v[150:151], 0, v[248:249]
	global_load_dwordx4 v[190:193], v[250:251], off
	global_load_dwordx4 v[194:197], v[250:251], off offset:16
	global_load_dwordx4 v[198:201], v[252:253], off
	global_load_dwordx4 v[202:205], v[252:253], off offset:16
	v_add_u32_e32 v246, 32, v164
	v_ashrrev_i32_e32 v247, 31, v246
	v_lshlrev_b64 v[248:249], 9, v[246:247]
	v_lshl_add_u64 v[250:251], v[152:153], 0, v[248:249]
	v_lshl_add_u64 v[252:253], v[150:151], 0, v[248:249]
	global_load_dwordx4 v[206:209], v[250:251], off
	global_load_dwordx4 v[210:213], v[250:251], off offset:16
	global_load_dwordx4 v[214:217], v[252:253], off
	global_load_dwordx4 v[218:221], v[252:253], off offset:16
	v_add_u32_e32 v246, 48, v164
	v_ashrrev_i32_e32 v247, 31, v246
	v_lshlrev_b64 v[248:249], 9, v[246:247]
	v_lshl_add_u64 v[250:251], v[152:153], 0, v[248:249]
	v_lshl_add_u64 v[252:253], v[150:151], 0, v[248:249]
	global_load_dwordx4 v[222:225], v[250:251], off
	global_load_dwordx4 v[226:229], v[250:251], off offset:16
	global_load_dwordx4 v[230:233], v[252:253], off
	global_load_dwordx4 v[234:237], v[252:253], off offset:16
	s_waitcnt vmcnt(12)
	v_pk_mul_f32 v[238:239], v[120:121], v[176:177]
	v_pk_mul_f32 v[240:241], v[118:119], v[174:175]
	v_pk_mul_f32 v[242:243], v[116:117], v[180:181]
	v_pk_mul_f32 v[244:245], v[114:115], v[178:179]
	v_pk_mul_f32 v[176:177], v[128:129], v[176:177]
	v_pk_mul_f32 v[174:175], v[126:127], v[174:175]
	v_pk_mul_f32 v[180:181], v[124:125], v[180:181]
	v_pk_mul_f32 v[178:179], v[122:123], v[178:179]
	v_pk_fma_f32 v[128:129], v[128:129], v[184:185], v[238:239] neg_lo:[0,0,1] neg_hi:[0,0,1]
	v_pk_fma_f32 v[126:127], v[126:127], v[182:183], v[240:241] neg_lo:[0,0,1] neg_hi:[0,0,1]
	v_pk_fma_f32 v[124:125], v[124:125], v[188:189], v[242:243] neg_lo:[0,0,1] neg_hi:[0,0,1]
	v_pk_fma_f32 v[122:123], v[122:123], v[186:187], v[244:245] neg_lo:[0,0,1] neg_hi:[0,0,1]
	v_pk_fma_f32 v[120:121], v[120:121], v[184:185], v[176:177]
	v_pk_fma_f32 v[118:119], v[118:119], v[182:183], v[174:175]
	v_pk_fma_f32 v[116:117], v[116:117], v[188:189], v[180:181]
	v_pk_fma_f32 v[114:115], v[114:115], v[186:187], v[178:179]
	v_pk_mul_f32 v[128:129], v[134:135], v[128:129] op_sel_hi:[0,1]
	v_pk_mul_f32 v[126:127], v[134:135], v[126:127] op_sel_hi:[0,1]
	v_pk_mul_f32 v[124:125], v[134:135], v[124:125] op_sel_hi:[0,1]
	v_pk_mul_f32 v[122:123], v[134:135], v[122:123] op_sel_hi:[0,1]
	v_pk_mul_f32 v[120:121], v[134:135], v[120:121] op_sel_hi:[0,1]
	v_pk_mul_f32 v[118:119], v[134:135], v[118:119] op_sel_hi:[0,1]
	v_pk_mul_f32 v[238:239], v[134:135], v[116:117] op_sel_hi:[0,1]
	v_pk_mul_f32 v[240:241], v[134:135], v[114:115] op_sel_hi:[0,1]
	v_cvt_pk_bf16_f32 v114, v126, v127
	v_cvt_pk_bf16_f32 v115, v128, v129
	v_cvt_pk_bf16_f32 v116, v122, v123
	v_cvt_pk_bf16_f32 v117, v124, v125
	v_cvt_pk_bf16_f32 v118, v118, v119
	v_cvt_pk_bf16_f32 v119, v120, v121
	v_cvt_pk_bf16_f32 v120, v240, v241
	v_cvt_pk_bf16_f32 v121, v238, v239
	v_add_u32_e32 v246, 128, v164
	v_ashrrev_i32_e32 v247, 31, v246
	v_lshlrev_b64 v[248:249], 9, v[246:247]
	v_lshl_add_u64 v[250:251], v[152:153], 0, v[248:249]
	v_lshl_add_u64 v[252:253], v[150:151], 0, v[248:249]
	global_load_dwordx4 v[174:177], v[250:251], off
	global_load_dwordx4 v[178:181], v[250:251], off offset:16
	global_load_dwordx4 v[182:185], v[252:253], off
	global_load_dwordx4 v[186:189], v[252:253], off offset:16
	s_waitcnt vmcnt(12)
	v_pk_mul_f32 v[238:239], v[104:105], v[192:193]
	v_pk_mul_f32 v[240:241], v[102:103], v[190:191]
	v_pk_mul_f32 v[242:243], v[100:101], v[196:197]
	v_pk_mul_f32 v[244:245], v[98:99], v[194:195]
	v_pk_mul_f32 v[192:193], v[112:113], v[192:193]
	v_pk_mul_f32 v[190:191], v[110:111], v[190:191]
	v_pk_mul_f32 v[196:197], v[108:109], v[196:197]
	v_pk_mul_f32 v[194:195], v[106:107], v[194:195]
	v_pk_fma_f32 v[112:113], v[112:113], v[200:201], v[238:239] neg_lo:[0,0,1] neg_hi:[0,0,1]
	v_pk_fma_f32 v[110:111], v[110:111], v[198:199], v[240:241] neg_lo:[0,0,1] neg_hi:[0,0,1]
	v_pk_fma_f32 v[108:109], v[108:109], v[204:205], v[242:243] neg_lo:[0,0,1] neg_hi:[0,0,1]
	v_pk_fma_f32 v[106:107], v[106:107], v[202:203], v[244:245] neg_lo:[0,0,1] neg_hi:[0,0,1]
	v_pk_fma_f32 v[104:105], v[104:105], v[200:201], v[192:193]
	v_pk_fma_f32 v[102:103], v[102:103], v[198:199], v[190:191]
	v_pk_fma_f32 v[100:101], v[100:101], v[204:205], v[196:197]
	v_pk_fma_f32 v[98:99], v[98:99], v[202:203], v[194:195]
	v_pk_mul_f32 v[112:113], v[134:135], v[112:113] op_sel_hi:[0,1]
	v_pk_mul_f32 v[110:111], v[134:135], v[110:111] op_sel_hi:[0,1]
	v_pk_mul_f32 v[108:109], v[134:135], v[108:109] op_sel_hi:[0,1]
	v_pk_mul_f32 v[106:107], v[134:135], v[106:107] op_sel_hi:[0,1]
	v_pk_mul_f32 v[104:105], v[134:135], v[104:105] op_sel_hi:[0,1]
	v_pk_mul_f32 v[102:103], v[134:135], v[102:103] op_sel_hi:[0,1]
	v_pk_mul_f32 v[238:239], v[134:135], v[100:101] op_sel_hi:[0,1]
	v_pk_mul_f32 v[240:241], v[134:135], v[98:99] op_sel_hi:[0,1]
	v_cvt_pk_bf16_f32 v98, v110, v111
	v_cvt_pk_bf16_f32 v99, v112, v113
	v_cvt_pk_bf16_f32 v100, v106, v107
	v_cvt_pk_bf16_f32 v101, v108, v109
	v_cvt_pk_bf16_f32 v102, v102, v103
	v_cvt_pk_bf16_f32 v103, v104, v105
	v_cvt_pk_bf16_f32 v104, v240, v241
	v_cvt_pk_bf16_f32 v105, v238, v239
	v_add_u32_e32 v246, 144, v164
	v_ashrrev_i32_e32 v247, 31, v246
	v_lshlrev_b64 v[248:249], 9, v[246:247]
	v_lshl_add_u64 v[250:251], v[152:153], 0, v[248:249]
	v_lshl_add_u64 v[252:253], v[150:151], 0, v[248:249]
	global_load_dwordx4 v[190:193], v[250:251], off
	global_load_dwordx4 v[194:197], v[250:251], off offset:16
	global_load_dwordx4 v[198:201], v[252:253], off
	global_load_dwordx4 v[202:205], v[252:253], off offset:16
	s_waitcnt vmcnt(12)
	v_pk_mul_f32 v[238:239], v[88:89], v[208:209]
	v_pk_mul_f32 v[240:241], v[86:87], v[206:207]
	v_pk_mul_f32 v[242:243], v[84:85], v[212:213]
	v_pk_mul_f32 v[244:245], v[82:83], v[210:211]
	v_pk_mul_f32 v[208:209], v[96:97], v[208:209]
	v_pk_mul_f32 v[206:207], v[94:95], v[206:207]
	v_pk_mul_f32 v[212:213], v[92:93], v[212:213]
	v_pk_mul_f32 v[210:211], v[90:91], v[210:211]
	v_pk_fma_f32 v[96:97], v[96:97], v[216:217], v[238:239] neg_lo:[0,0,1] neg_hi:[0,0,1]
	v_pk_fma_f32 v[94:95], v[94:95], v[214:215], v[240:241] neg_lo:[0,0,1] neg_hi:[0,0,1]
	v_pk_fma_f32 v[92:93], v[92:93], v[220:221], v[242:243] neg_lo:[0,0,1] neg_hi:[0,0,1]
	v_pk_fma_f32 v[90:91], v[90:91], v[218:219], v[244:245] neg_lo:[0,0,1] neg_hi:[0,0,1]
	v_pk_fma_f32 v[88:89], v[88:89], v[216:217], v[208:209]
	v_pk_fma_f32 v[86:87], v[86:87], v[214:215], v[206:207]
	v_pk_fma_f32 v[84:85], v[84:85], v[220:221], v[212:213]
	v_pk_fma_f32 v[82:83], v[82:83], v[218:219], v[210:211]
	v_pk_mul_f32 v[96:97], v[134:135], v[96:97] op_sel_hi:[0,1]
	v_pk_mul_f32 v[94:95], v[134:135], v[94:95] op_sel_hi:[0,1]
	v_pk_mul_f32 v[92:93], v[134:135], v[92:93] op_sel_hi:[0,1]
	v_pk_mul_f32 v[90:91], v[134:135], v[90:91] op_sel_hi:[0,1]
	v_pk_mul_f32 v[88:89], v[134:135], v[88:89] op_sel_hi:[0,1]
	v_pk_mul_f32 v[86:87], v[134:135], v[86:87] op_sel_hi:[0,1]
	v_pk_mul_f32 v[238:239], v[134:135], v[84:85] op_sel_hi:[0,1]
	v_pk_mul_f32 v[240:241], v[134:135], v[82:83] op_sel_hi:[0,1]
	v_cvt_pk_bf16_f32 v82, v94, v95
	v_cvt_pk_bf16_f32 v83, v96, v97
	v_cvt_pk_bf16_f32 v84, v90, v91
	v_cvt_pk_bf16_f32 v85, v92, v93
	v_cvt_pk_bf16_f32 v86, v86, v87
	v_cvt_pk_bf16_f32 v87, v88, v89
	v_cvt_pk_bf16_f32 v88, v240, v241
	v_cvt_pk_bf16_f32 v89, v238, v239
	v_add_u32_e32 v246, 160, v164
	v_ashrrev_i32_e32 v247, 31, v246
	v_lshlrev_b64 v[248:249], 9, v[246:247]
	v_lshl_add_u64 v[250:251], v[152:153], 0, v[248:249]
	v_lshl_add_u64 v[252:253], v[150:151], 0, v[248:249]
	global_load_dwordx4 v[206:209], v[250:251], off
	global_load_dwordx4 v[210:213], v[250:251], off offset:16
	global_load_dwordx4 v[214:217], v[252:253], off
	global_load_dwordx4 v[218:221], v[252:253], off offset:16
	s_waitcnt vmcnt(12)
	v_pk_mul_f32 v[238:239], v[72:73], v[224:225]
	v_pk_mul_f32 v[240:241], v[70:71], v[222:223]
	v_pk_mul_f32 v[242:243], v[68:69], v[228:229]
	v_pk_mul_f32 v[244:245], v[66:67], v[226:227]
	v_pk_mul_f32 v[224:225], v[80:81], v[224:225]
	v_pk_mul_f32 v[222:223], v[78:79], v[222:223]
	v_pk_mul_f32 v[228:229], v[76:77], v[228:229]
	v_pk_mul_f32 v[226:227], v[74:75], v[226:227]
	v_pk_fma_f32 v[80:81], v[80:81], v[232:233], v[238:239] neg_lo:[0,0,1] neg_hi:[0,0,1]
	v_pk_fma_f32 v[78:79], v[78:79], v[230:231], v[240:241] neg_lo:[0,0,1] neg_hi:[0,0,1]
	v_pk_fma_f32 v[76:77], v[76:77], v[236:237], v[242:243] neg_lo:[0,0,1] neg_hi:[0,0,1]
	v_pk_fma_f32 v[74:75], v[74:75], v[234:235], v[244:245] neg_lo:[0,0,1] neg_hi:[0,0,1]
	v_pk_fma_f32 v[72:73], v[72:73], v[232:233], v[224:225]
	v_pk_fma_f32 v[70:71], v[70:71], v[230:231], v[222:223]
	v_pk_fma_f32 v[68:69], v[68:69], v[236:237], v[228:229]
	v_pk_fma_f32 v[66:67], v[66:67], v[234:235], v[226:227]
	v_pk_mul_f32 v[80:81], v[134:135], v[80:81] op_sel_hi:[0,1]
	v_pk_mul_f32 v[78:79], v[134:135], v[78:79] op_sel_hi:[0,1]
	v_pk_mul_f32 v[76:77], v[134:135], v[76:77] op_sel_hi:[0,1]
	v_pk_mul_f32 v[74:75], v[134:135], v[74:75] op_sel_hi:[0,1]
	v_pk_mul_f32 v[72:73], v[134:135], v[72:73] op_sel_hi:[0,1]
	v_pk_mul_f32 v[70:71], v[134:135], v[70:71] op_sel_hi:[0,1]
	v_pk_mul_f32 v[238:239], v[134:135], v[68:69] op_sel_hi:[0,1]
	v_pk_mul_f32 v[240:241], v[134:135], v[66:67] op_sel_hi:[0,1]
	v_cvt_pk_bf16_f32 v66, v78, v79
	v_cvt_pk_bf16_f32 v67, v80, v81
	v_cvt_pk_bf16_f32 v68, v74, v75
	v_cvt_pk_bf16_f32 v69, v76, v77
	v_cvt_pk_bf16_f32 v70, v70, v71
	v_cvt_pk_bf16_f32 v71, v72, v73
	v_cvt_pk_bf16_f32 v72, v240, v241
	v_cvt_pk_bf16_f32 v73, v238, v239
	v_add_u32_e32 v246, 176, v164
	v_ashrrev_i32_e32 v247, 31, v246
	v_lshlrev_b64 v[248:249], 9, v[246:247]
	v_lshl_add_u64 v[250:251], v[152:153], 0, v[248:249]
	v_lshl_add_u64 v[252:253], v[150:151], 0, v[248:249]
	global_load_dwordx4 v[222:225], v[250:251], off
	global_load_dwordx4 v[226:229], v[250:251], off offset:16
	global_load_dwordx4 v[230:233], v[252:253], off
	global_load_dwordx4 v[234:237], v[252:253], off offset:16
	s_waitcnt vmcnt(12)
	v_pk_mul_f32 v[238:239], v[56:57], v[176:177]
	v_pk_mul_f32 v[240:241], v[54:55], v[174:175]
	v_pk_mul_f32 v[242:243], v[52:53], v[180:181]
	v_pk_mul_f32 v[244:245], v[50:51], v[178:179]
	v_pk_mul_f32 v[176:177], v[64:65], v[176:177]
	v_pk_mul_f32 v[174:175], v[62:63], v[174:175]
	v_pk_mul_f32 v[180:181], v[60:61], v[180:181]
	v_pk_mul_f32 v[178:179], v[58:59], v[178:179]
	v_pk_fma_f32 v[64:65], v[64:65], v[184:185], v[238:239] neg_lo:[0,0,1] neg_hi:[0,0,1]
	v_pk_fma_f32 v[62:63], v[62:63], v[182:183], v[240:241] neg_lo:[0,0,1] neg_hi:[0,0,1]
	v_pk_fma_f32 v[60:61], v[60:61], v[188:189], v[242:243] neg_lo:[0,0,1] neg_hi:[0,0,1]
	v_pk_fma_f32 v[58:59], v[58:59], v[186:187], v[244:245] neg_lo:[0,0,1] neg_hi:[0,0,1]
	v_pk_fma_f32 v[56:57], v[56:57], v[184:185], v[176:177]
	v_pk_fma_f32 v[54:55], v[54:55], v[182:183], v[174:175]
	v_pk_fma_f32 v[52:53], v[52:53], v[188:189], v[180:181]
	v_pk_fma_f32 v[50:51], v[50:51], v[186:187], v[178:179]
	v_pk_mul_f32 v[64:65], v[134:135], v[64:65] op_sel_hi:[0,1]
	v_pk_mul_f32 v[62:63], v[134:135], v[62:63] op_sel_hi:[0,1]
	v_pk_mul_f32 v[60:61], v[134:135], v[60:61] op_sel_hi:[0,1]
	v_pk_mul_f32 v[58:59], v[134:135], v[58:59] op_sel_hi:[0,1]
	v_pk_mul_f32 v[56:57], v[134:135], v[56:57] op_sel_hi:[0,1]
	v_pk_mul_f32 v[54:55], v[134:135], v[54:55] op_sel_hi:[0,1]
	v_pk_mul_f32 v[238:239], v[134:135], v[52:53] op_sel_hi:[0,1]
	v_pk_mul_f32 v[240:241], v[134:135], v[50:51] op_sel_hi:[0,1]
	v_cvt_pk_bf16_f32 v50, v62, v63
	v_cvt_pk_bf16_f32 v51, v64, v65
	v_cvt_pk_bf16_f32 v52, v58, v59
	v_cvt_pk_bf16_f32 v53, v60, v61
	v_cvt_pk_bf16_f32 v54, v54, v55
	v_cvt_pk_bf16_f32 v55, v56, v57
	v_cvt_pk_bf16_f32 v56, v240, v241
	v_cvt_pk_bf16_f32 v57, v238, v239
	s_waitcnt vmcnt(8)
	v_pk_mul_f32 v[238:239], v[40:41], v[192:193]
	v_pk_mul_f32 v[240:241], v[38:39], v[190:191]
	v_pk_mul_f32 v[242:243], v[36:37], v[196:197]
	v_pk_mul_f32 v[244:245], v[34:35], v[194:195]
	v_pk_mul_f32 v[192:193], v[48:49], v[192:193]
	v_pk_mul_f32 v[190:191], v[46:47], v[190:191]
	v_pk_mul_f32 v[196:197], v[44:45], v[196:197]
	v_pk_mul_f32 v[194:195], v[42:43], v[194:195]
	v_pk_fma_f32 v[48:49], v[48:49], v[200:201], v[238:239] neg_lo:[0,0,1] neg_hi:[0,0,1]
	v_pk_fma_f32 v[46:47], v[46:47], v[198:199], v[240:241] neg_lo:[0,0,1] neg_hi:[0,0,1]
	v_pk_fma_f32 v[44:45], v[44:45], v[204:205], v[242:243] neg_lo:[0,0,1] neg_hi:[0,0,1]
	v_pk_fma_f32 v[42:43], v[42:43], v[202:203], v[244:245] neg_lo:[0,0,1] neg_hi:[0,0,1]
	v_pk_fma_f32 v[40:41], v[40:41], v[200:201], v[192:193]
	v_pk_fma_f32 v[38:39], v[38:39], v[198:199], v[190:191]
	v_pk_fma_f32 v[36:37], v[36:37], v[204:205], v[196:197]
	v_pk_fma_f32 v[34:35], v[34:35], v[202:203], v[194:195]
	v_pk_mul_f32 v[48:49], v[134:135], v[48:49] op_sel_hi:[0,1]
	v_pk_mul_f32 v[46:47], v[134:135], v[46:47] op_sel_hi:[0,1]
	v_pk_mul_f32 v[44:45], v[134:135], v[44:45] op_sel_hi:[0,1]
	v_pk_mul_f32 v[42:43], v[134:135], v[42:43] op_sel_hi:[0,1]
	v_pk_mul_f32 v[40:41], v[134:135], v[40:41] op_sel_hi:[0,1]
	v_pk_mul_f32 v[38:39], v[134:135], v[38:39] op_sel_hi:[0,1]
	v_pk_mul_f32 v[238:239], v[134:135], v[36:37] op_sel_hi:[0,1]
	v_pk_mul_f32 v[240:241], v[134:135], v[34:35] op_sel_hi:[0,1]
	v_cvt_pk_bf16_f32 v34, v46, v47
	v_cvt_pk_bf16_f32 v35, v48, v49
	v_cvt_pk_bf16_f32 v36, v42, v43
	v_cvt_pk_bf16_f32 v37, v44, v45
	v_cvt_pk_bf16_f32 v38, v38, v39
	v_cvt_pk_bf16_f32 v39, v40, v41
	v_cvt_pk_bf16_f32 v40, v240, v241
	v_cvt_pk_bf16_f32 v41, v238, v239
	s_waitcnt vmcnt(4)
	v_pk_mul_f32 v[238:239], v[24:25], v[208:209]
	v_pk_mul_f32 v[240:241], v[22:23], v[206:207]
	v_pk_mul_f32 v[242:243], v[20:21], v[212:213]
	v_pk_mul_f32 v[244:245], v[18:19], v[210:211]
	v_pk_mul_f32 v[208:209], v[32:33], v[208:209]
	v_pk_mul_f32 v[206:207], v[30:31], v[206:207]
	v_pk_mul_f32 v[212:213], v[28:29], v[212:213]
	v_pk_mul_f32 v[210:211], v[26:27], v[210:211]
	v_pk_fma_f32 v[32:33], v[32:33], v[216:217], v[238:239] neg_lo:[0,0,1] neg_hi:[0,0,1]
	v_pk_fma_f32 v[30:31], v[30:31], v[214:215], v[240:241] neg_lo:[0,0,1] neg_hi:[0,0,1]
	v_pk_fma_f32 v[28:29], v[28:29], v[220:221], v[242:243] neg_lo:[0,0,1] neg_hi:[0,0,1]
	v_pk_fma_f32 v[26:27], v[26:27], v[218:219], v[244:245] neg_lo:[0,0,1] neg_hi:[0,0,1]
	v_pk_fma_f32 v[24:25], v[24:25], v[216:217], v[208:209]
	v_pk_fma_f32 v[22:23], v[22:23], v[214:215], v[206:207]
	v_pk_fma_f32 v[20:21], v[20:21], v[220:221], v[212:213]
	v_pk_fma_f32 v[18:19], v[18:19], v[218:219], v[210:211]
	v_pk_mul_f32 v[32:33], v[134:135], v[32:33] op_sel_hi:[0,1]
	v_pk_mul_f32 v[30:31], v[134:135], v[30:31] op_sel_hi:[0,1]
	v_pk_mul_f32 v[28:29], v[134:135], v[28:29] op_sel_hi:[0,1]
	v_pk_mul_f32 v[26:27], v[134:135], v[26:27] op_sel_hi:[0,1]
	v_pk_mul_f32 v[24:25], v[134:135], v[24:25] op_sel_hi:[0,1]
	v_pk_mul_f32 v[22:23], v[134:135], v[22:23] op_sel_hi:[0,1]
	v_pk_mul_f32 v[238:239], v[134:135], v[20:21] op_sel_hi:[0,1]
	v_pk_mul_f32 v[240:241], v[134:135], v[18:19] op_sel_hi:[0,1]
	v_cvt_pk_bf16_f32 v18, v30, v31
	v_cvt_pk_bf16_f32 v19, v32, v33
	v_cvt_pk_bf16_f32 v20, v26, v27
	v_cvt_pk_bf16_f32 v21, v28, v29
	v_cvt_pk_bf16_f32 v22, v22, v23
	v_cvt_pk_bf16_f32 v23, v24, v25
	v_cvt_pk_bf16_f32 v24, v240, v241
	v_cvt_pk_bf16_f32 v25, v238, v239
	s_waitcnt vmcnt(0)
	v_pk_mul_f32 v[238:239], v[8:9], v[224:225]
	v_pk_mul_f32 v[240:241], v[6:7], v[222:223]
	v_pk_mul_f32 v[242:243], v[4:5], v[228:229]
	v_pk_mul_f32 v[244:245], v[2:3], v[226:227]
	v_pk_mul_f32 v[224:225], v[16:17], v[224:225]
	v_pk_mul_f32 v[222:223], v[14:15], v[222:223]
	v_pk_mul_f32 v[228:229], v[12:13], v[228:229]
	v_pk_mul_f32 v[226:227], v[10:11], v[226:227]
	v_pk_fma_f32 v[16:17], v[16:17], v[232:233], v[238:239] neg_lo:[0,0,1] neg_hi:[0,0,1]
	v_pk_fma_f32 v[14:15], v[14:15], v[230:231], v[240:241] neg_lo:[0,0,1] neg_hi:[0,0,1]
	v_pk_fma_f32 v[12:13], v[12:13], v[236:237], v[242:243] neg_lo:[0,0,1] neg_hi:[0,0,1]
	v_pk_fma_f32 v[10:11], v[10:11], v[234:235], v[244:245] neg_lo:[0,0,1] neg_hi:[0,0,1]
	v_pk_fma_f32 v[8:9], v[8:9], v[232:233], v[224:225]
	v_pk_fma_f32 v[6:7], v[6:7], v[230:231], v[222:223]
	v_pk_fma_f32 v[4:5], v[4:5], v[236:237], v[228:229]
	v_pk_fma_f32 v[2:3], v[2:3], v[234:235], v[226:227]
	v_pk_mul_f32 v[16:17], v[134:135], v[16:17] op_sel_hi:[0,1]
	v_pk_mul_f32 v[14:15], v[134:135], v[14:15] op_sel_hi:[0,1]
	v_pk_mul_f32 v[12:13], v[134:135], v[12:13] op_sel_hi:[0,1]
	v_pk_mul_f32 v[10:11], v[134:135], v[10:11] op_sel_hi:[0,1]
	v_pk_mul_f32 v[132:133], v[134:135], v[8:9] op_sel_hi:[0,1]
	v_pk_mul_f32 v[130:131], v[134:135], v[6:7] op_sel_hi:[0,1]
	v_pk_mul_f32 v[136:137], v[134:135], v[4:5] op_sel_hi:[0,1]
	v_pk_mul_f32 v[134:135], v[134:135], v[2:3] op_sel_hi:[0,1]
	v_cvt_pk_bf16_f32 v2, v14, v15
	v_cvt_pk_bf16_f32 v3, v16, v17
	v_cvt_pk_bf16_f32 v4, v10, v11
	v_cvt_pk_bf16_f32 v5, v12, v13
	v_mov_b32_e32 v246, v164
	v_ashrrev_i32_e32 v247, 31, v246
	v_lshlrev_b64 v[248:249], 12, v[246:247]
	v_lshl_add_u64 v[250:251], v[166:167], 0, v[248:249]
	global_store_dwordx4 v[250:251], v[114:117], off nt
	global_store_dwordx4 v[250:251], v[118:121], off offset:256 nt
	v_add_u32_e32 v246, 16, v164
	v_ashrrev_i32_e32 v247, 31, v246
	v_lshlrev_b64 v[248:249], 12, v[246:247]
	v_lshl_add_u64 v[250:251], v[166:167], 0, v[248:249]
	global_store_dwordx4 v[250:251], v[98:101], off nt
	global_store_dwordx4 v[250:251], v[102:105], off offset:256 nt
	v_add_u32_e32 v246, 32, v164
	v_ashrrev_i32_e32 v247, 31, v246
	v_lshlrev_b64 v[248:249], 12, v[246:247]
	v_lshl_add_u64 v[250:251], v[166:167], 0, v[248:249]
	global_store_dwordx4 v[250:251], v[82:85], off nt
	global_store_dwordx4 v[250:251], v[86:89], off offset:256 nt
	v_add_u32_e32 v246, 48, v164
	v_ashrrev_i32_e32 v247, 31, v246
	v_lshlrev_b64 v[248:249], 12, v[246:247]
	v_lshl_add_u64 v[250:251], v[166:167], 0, v[248:249]
	global_store_dwordx4 v[250:251], v[66:69], off nt
	global_store_dwordx4 v[250:251], v[70:73], off offset:256 nt
	v_add_u32_e32 v246, 128, v164
	v_ashrrev_i32_e32 v247, 31, v246
	v_lshlrev_b64 v[248:249], 12, v[246:247]
	v_lshl_add_u64 v[250:251], v[166:167], 0, v[248:249]
	global_store_dwordx4 v[250:251], v[50:53], off nt
	global_store_dwordx4 v[250:251], v[54:57], off offset:256 nt
	v_add_u32_e32 v246, 144, v164
	v_ashrrev_i32_e32 v247, 31, v246
	v_lshlrev_b64 v[248:249], 12, v[246:247]
	v_lshl_add_u64 v[250:251], v[166:167], 0, v[248:249]
	global_store_dwordx4 v[250:251], v[34:37], off nt
	global_store_dwordx4 v[250:251], v[38:41], off offset:256 nt
	v_add_u32_e32 v246, 160, v164
	v_ashrrev_i32_e32 v247, 31, v246
	v_lshlrev_b64 v[248:249], 12, v[246:247]
	v_lshl_add_u64 v[250:251], v[166:167], 0, v[248:249]
	global_store_dwordx4 v[250:251], v[18:21], off nt
	global_store_dwordx4 v[250:251], v[22:25], off offset:256 nt
	v_add_u32_e32 v246, 176, v164
	v_ashrrev_i32_e32 v247, 31, v246
	v_lshlrev_b64 v[248:249], 12, v[246:247]
	v_lshl_add_u64 v[166:167], v[166:167], 0, v[248:249]
	global_store_dwordx4 v[166:167], v[2:5], off nt
.LBB0_505:
	s_nop 1
	v_cvt_pk_bf16_f32 v2, v130, v131
	v_cvt_pk_bf16_f32 v3, v132, v133
	v_cvt_pk_bf16_f32 v4, v134, v135
	v_cvt_pk_bf16_f32 v5, v136, v137
	s_andn2_b64 vcc, exec, s[4:5]
	s_mov_b64 s[4:5], -1
	global_store_dwordx4 v[166:167], v[2:5], off offset:256 nt
	s_cbranch_vccnz .LBB0_462
	s_andn2_b64 vcc, exec, s[8:9]
	s_cbranch_vccnz .LBB0_461
	s_barrier
	s_branch .LBB0_461
	s_nop 0
	s_nop 0
	s_nop 0
	s_nop 0
	s_nop 0
	s_nop 0
	s_nop 0
	s_nop 0
	s_nop 0
	s_nop 0
	s_nop 0
	s_nop 0
	s_nop 0
	s_nop 0
